# Y2: attention loop: softmax denominator kept as per-half partial sums and combined once at loop exit; end-of-Y rescale test reuses the uniform flag in vcc; on top of PZ1
# speedup vs baseline: 1.0167x; 1.0004x over previous
.LBB0_629:
	v_max_f32_e32 v148, v84, v85
	v_max_f32_e32 v149, v68, v69
	v_max3_f32 v148, v148, v86, v87
	v_max3_f32 v149, v149, v70, v71
	v_max3_f32 v148, v148, v88, v89
	v_max3_f32 v149, v149, v72, v73
	v_max3_f32 v148, v148, v90, v91
	v_max3_f32 v149, v149, v74, v75
	v_max3_f32 v148, v148, v92, v93
	v_max3_f32 v149, v149, v76, v77
	v_max3_f32 v148, v148, v94, v95
	v_max3_f32 v149, v149, v78, v79
	v_max3_f32 v148, v148, v96, v97
	v_max3_f32 v149, v149, v80, v81
	v_max3_f32 v148, v148, v98, v99
	v_max3_f32 v149, v149, v82, v83
	v_max_f32_e32 v148, v148, v149
	v_mov_b32_e32 v149, v148
	s_nop 1
	v_permlane32_swap_b32_e32 v148, v149
	v_max_f32_e32 v148, v148, v149
	v_sub_f32_e32 v149, v148, v182
	v_cmp_ge_f32_e32 vcc, s23, v149
	v_max_f32_e32 v148, v182, v148
	s_cmp_eq_u64 vcc, exec
	s_cselect_b64 vcc, -1, 0
	v_sub_f32_e32 v150, v182, v148
	v_cndmask_b32_e32 v182, v148, v182, vcc
	v_mul_f32_e32 v148, 0xbe0293ee, v182
	v_fmamk_f32 v84, v84, 0x3e0293ee, v148
	v_fmamk_f32 v85, v85, 0x3e0293ee, v148
	v_fmamk_f32 v86, v86, 0x3e0293ee, v148
	v_fmamk_f32 v87, v87, 0x3e0293ee, v148
	v_fmamk_f32 v88, v88, 0x3e0293ee, v148
	v_fmamk_f32 v89, v89, 0x3e0293ee, v148
	v_fmamk_f32 v90, v90, 0x3e0293ee, v148
	v_fmamk_f32 v91, v91, 0x3e0293ee, v148
	v_fmamk_f32 v92, v92, 0x3e0293ee, v148
	v_fmamk_f32 v93, v93, 0x3e0293ee, v148
	v_fmamk_f32 v94, v94, 0x3e0293ee, v148
	v_fmamk_f32 v95, v95, 0x3e0293ee, v148
	v_fmamk_f32 v96, v96, 0x3e0293ee, v148
	v_fmamk_f32 v97, v97, 0x3e0293ee, v148
	v_fmamk_f32 v98, v98, 0x3e0293ee, v148
	v_fmamk_f32 v99, v99, 0x3e0293ee, v148
	v_fmamk_f32 v68, v68, 0x3e0293ee, v148
	v_fmamk_f32 v69, v69, 0x3e0293ee, v148
	v_fmamk_f32 v70, v70, 0x3e0293ee, v148
	v_fmamk_f32 v71, v71, 0x3e0293ee, v148
	v_fmamk_f32 v72, v72, 0x3e0293ee, v148
	v_fmamk_f32 v73, v73, 0x3e0293ee, v148
	v_fmamk_f32 v74, v74, 0x3e0293ee, v148
	v_fmamk_f32 v75, v75, 0x3e0293ee, v148
	v_fmamk_f32 v76, v76, 0x3e0293ee, v148
	v_fmamk_f32 v77, v77, 0x3e0293ee, v148
	v_fmamk_f32 v78, v78, 0x3e0293ee, v148
	v_fmamk_f32 v79, v79, 0x3e0293ee, v148
	v_fmamk_f32 v80, v80, 0x3e0293ee, v148
	v_fmamk_f32 v81, v81, 0x3e0293ee, v148
	v_fmamk_f32 v82, v82, 0x3e0293ee, v148
	v_fmac_f32_e32 v148, 0x3e0293ee, v83
	v_exp_f32_e32 v83, v84
	v_exp_f32_e32 v84, v85
	v_exp_f32_e32 v85, v86
	v_add_f32_e32 v149, v84, v83
	v_exp_f32_e32 v86, v87
	v_add_f32_e32 v149, v85, v149
	v_exp_f32_e32 v87, v88
	v_add_f32_e32 v149, v86, v149
	v_exp_f32_e32 v88, v89
	v_add_f32_e32 v149, v87, v149
	v_exp_f32_e32 v89, v90
	v_add_f32_e32 v149, v88, v149
	v_exp_f32_e32 v90, v91
	v_add_f32_e32 v149, v89, v149
	v_exp_f32_e32 v91, v92
	v_add_f32_e32 v149, v90, v149
	v_exp_f32_e32 v92, v93
	v_add_f32_e32 v149, v91, v149
	v_exp_f32_e32 v93, v94
	v_add_f32_e32 v149, v92, v149
	v_exp_f32_e32 v94, v95
	v_add_f32_e32 v149, v93, v149
	v_exp_f32_e32 v95, v96
	v_add_f32_e32 v149, v94, v149
	v_exp_f32_e32 v96, v97
	v_add_f32_e32 v149, v95, v149
	v_exp_f32_e32 v97, v98
	v_add_f32_e32 v149, v96, v149
	v_exp_f32_e32 v98, v99
	v_add_f32_e32 v149, v97, v149
	v_exp_f32_e32 v99, v148
	v_add_f32_e32 v149, v98, v149
	v_exp_f32_e32 v68, v68
	v_exp_f32_e32 v69, v69
	v_add_f32_e32 v149, v68, v149
	v_exp_f32_e32 v70, v70
	v_add_f32_e32 v149, v69, v149
	v_exp_f32_e32 v71, v71
	v_add_f32_e32 v149, v70, v149
	v_exp_f32_e32 v72, v72
	v_add_f32_e32 v149, v71, v149
	v_exp_f32_e32 v73, v73
	v_add_f32_e32 v149, v72, v149
	v_exp_f32_e32 v74, v74
	v_add_f32_e32 v149, v73, v149
	v_exp_f32_e32 v75, v75
	v_add_f32_e32 v149, v74, v149
	v_exp_f32_e32 v76, v76
	v_add_f32_e32 v149, v75, v149
	v_exp_f32_e32 v77, v77
	v_add_f32_e32 v149, v76, v149
	v_exp_f32_e32 v78, v78
	v_add_f32_e32 v149, v77, v149
	v_exp_f32_e32 v79, v79
	v_add_f32_e32 v149, v78, v149
	v_exp_f32_e32 v80, v80
	v_add_f32_e32 v149, v79, v149
	v_exp_f32_e32 v81, v81
	v_add_f32_e32 v149, v80, v149
	v_exp_f32_e32 v82, v82
	v_add_f32_e32 v149, v81, v149
	v_mul_f32_e32 v150, 0x3e0293ee, v150
	v_add_f32_e32 v149, v82, v149
	v_exp_f32_e32 v150, v150
	v_add_f32_e32 v185, v99, v149
	v_cndmask_b32_e64 v184, v150, 1.0, vcc
	v_cvt_pk_bf16_f32 v148, v83, v84
	v_cvt_pk_bf16_f32 v149, v85, v86
	v_cvt_pk_bf16_f32 v150, v87, v88
	v_cvt_pk_bf16_f32 v151, v89, v90
	v_cvt_pk_bf16_f32 v152, v91, v92
	v_cvt_pk_bf16_f32 v153, v93, v94
	v_cvt_pk_bf16_f32 v154, v95, v96
	v_cvt_pk_bf16_f32 v155, v97, v98
	v_cvt_pk_bf16_f32 v156, v68, v69
	v_cvt_pk_bf16_f32 v157, v70, v71
	v_cvt_pk_bf16_f32 v158, v72, v73
	v_cvt_pk_bf16_f32 v159, v74, v75
	v_cvt_pk_bf16_f32 v160, v76, v77
	v_cvt_pk_bf16_f32 v161, v78, v79
	v_cvt_pk_bf16_f32 v162, v80, v81
	v_cvt_pk_bf16_f32 v163, v82, v99
	s_mov_b32 s53, s52
	s_cbranch_vccnz .LBB0_633
	s_and_saveexec_b64 s[16:17], s[38:39]
	ds_write_b32 v172, v184 offset:128
	s_or_b64 exec, exec, s[16:17]
	s_waitcnt lgkmcnt(0)
	v_add_u32_e32 v80, v171, v168
	ds_read_b128 v[68:71], v80 offset:224
	ds_read_b128 v[72:75], v80 offset:192
	ds_read_b128 v[76:79], v80 offset:160
	ds_read_b128 v[80:83], v80 offset:128
	s_waitcnt lgkmcnt(3)
	v_pk_mul_f32 v[16:17], v[16:17], v[68:69]
	s_waitcnt lgkmcnt(2)
	v_pk_mul_f32 v[12:13], v[12:13], v[72:73]
	s_waitcnt lgkmcnt(1)
	v_pk_mul_f32 v[8:9], v[8:9], v[76:77]
	v_pk_mul_f32 v[18:19], v[18:19], v[70:71]
	v_pk_mul_f32 v[14:15], v[14:15], v[74:75]
	v_pk_mul_f32 v[10:11], v[10:11], v[78:79]
	s_waitcnt lgkmcnt(0)
	v_pk_mul_f32 v[6:7], v[6:7], v[82:83]
	v_pk_mul_f32 v[4:5], v[4:5], v[80:81]
	v_pk_mul_f32 v[64:65], v[64:65], v[68:69]
	v_pk_mul_f32 v[60:61], v[60:61], v[72:73]
	v_pk_mul_f32 v[56:57], v[56:57], v[76:77]
	v_pk_mul_f32 v[66:67], v[66:67], v[70:71]
	v_pk_mul_f32 v[62:63], v[62:63], v[74:75]
	v_pk_mul_f32 v[58:59], v[58:59], v[78:79]
	v_pk_mul_f32 v[54:55], v[54:55], v[82:83]
	v_pk_mul_f32 v[52:53], v[52:53], v[80:81]
	v_pk_mul_f32 v[48:49], v[48:49], v[68:69]
	v_pk_mul_f32 v[44:45], v[44:45], v[72:73]
	v_pk_mul_f32 v[40:41], v[40:41], v[76:77]
	v_pk_mul_f32 v[50:51], v[50:51], v[70:71]
	v_pk_mul_f32 v[46:47], v[46:47], v[74:75]
	v_pk_mul_f32 v[42:43], v[42:43], v[78:79]
	v_pk_mul_f32 v[38:39], v[38:39], v[82:83]
	v_pk_mul_f32 v[36:37], v[36:37], v[80:81]
	v_pk_mul_f32 v[32:33], v[32:33], v[68:69]
	v_pk_mul_f32 v[28:29], v[28:29], v[72:73]
	v_pk_mul_f32 v[24:25], v[24:25], v[76:77]
	v_pk_mul_f32 v[34:35], v[34:35], v[70:71]
	v_pk_mul_f32 v[30:31], v[30:31], v[74:75]
	v_pk_mul_f32 v[26:27], v[26:27], v[78:79]
	v_pk_mul_f32 v[22:23], v[22:23], v[82:83]
	v_pk_mul_f32 v[20:21], v[20:21], v[80:81]

.LBB0_635:
	s_waitcnt lgkmcnt(0)
	s_barrier
	v_fma_f32 v183, v183, v184, v185
	s_add_i32 s50, s50, 64
	s_cmp_eq_u32 s46, s48
	s_cbranch_scc1 .LBB0_637
	s_mov_b32 s52, s49
	s_mov_b32 s49, s51
	s_mov_b32 s51, s53
	s_branch .LBB0_629
.LBB0_637:
	v_mov_b32_e32 v148, v183
	v_mov_b32_e32 v186, v183
	s_nop 1
	v_permlane32_swap_b32_e32 v148, v186
	v_add_f32_e32 v148, v148, v186
	v_max_f32_e32 v2, v85, v85
	s_waitcnt vmcnt(0)
	v_max_f32_e32 v132, v84, v84
	v_max_f32_e32 v2, v132, v2
	v_max3_f32 v2, v2, v86, v87
	v_max3_f32 v2, v2, v88, v89
	v_max3_f32 v2, v2, v90, v91
	v_max3_f32 v2, v2, v92, v93
	v_max3_f32 v2, v2, v94, v95
	v_max3_f32 v2, v2, v96, v97
	v_max3_f32 v2, v2, v98, v99
	v_max3_f32 v2, v2, v68, v69
	v_max3_f32 v2, v2, v70, v71
	v_max3_f32 v2, v2, v72, v73
	v_max3_f32 v2, v2, v74, v75
	v_max3_f32 v2, v2, v76, v77
	v_max3_f32 v2, v2, v78, v79
	v_max3_f32 v2, v2, v80, v81
	v_max3_f32 v2, v2, v82, v83
	v_mov_b32_e32 v132, v2
	s_nop 1
	v_permlane32_swap_b32_e32 v2, v132
	v_max_f32_e32 v132, v132, v132
	v_max_f32_e32 v2, v2, v2
	v_max_f32_e32 v2, v2, v132
	v_sub_f32_e32 v132, v2, v182
	v_cmp_ge_f32_e32 vcc, s23, v132
	v_max_f32_e32 v133, v182, v182
	s_cmp_eq_u64 vcc, exec
	v_max_f32_e32 v133, v133, v2
	s_cselect_b64 vcc, -1, 0
	v_cndmask_b32_e32 v151, v133, v182, vcc
	v_mul_f32_e32 v132, 0xbe0293ee, v151
	v_fmamk_f32 v84, v84, 0x3e0293ee, v132
	v_fmamk_f32 v85, v85, 0x3e0293ee, v132
	v_fmamk_f32 v86, v86, 0x3e0293ee, v132
	v_fmamk_f32 v87, v87, 0x3e0293ee, v132
	v_fmamk_f32 v88, v88, 0x3e0293ee, v132
	v_fmamk_f32 v89, v89, 0x3e0293ee, v132
	v_fmamk_f32 v90, v90, 0x3e0293ee, v132
	v_fmamk_f32 v91, v91, 0x3e0293ee, v132
	v_fmamk_f32 v92, v92, 0x3e0293ee, v132
	v_fmamk_f32 v93, v93, 0x3e0293ee, v132
	v_fmamk_f32 v94, v94, 0x3e0293ee, v132
	v_fmamk_f32 v95, v95, 0x3e0293ee, v132
	v_fmamk_f32 v96, v96, 0x3e0293ee, v132
	v_fmamk_f32 v97, v97, 0x3e0293ee, v132
	v_fmamk_f32 v98, v98, 0x3e0293ee, v132
	v_fmamk_f32 v99, v99, 0x3e0293ee, v132
	v_fmamk_f32 v68, v68, 0x3e0293ee, v132
	v_fmamk_f32 v69, v69, 0x3e0293ee, v132
	v_fmamk_f32 v70, v70, 0x3e0293ee, v132
	v_fmamk_f32 v71, v71, 0x3e0293ee, v132
	v_fmamk_f32 v72, v72, 0x3e0293ee, v132
	v_fmamk_f32 v73, v73, 0x3e0293ee, v132
	v_fmamk_f32 v74, v74, 0x3e0293ee, v132
	v_fmamk_f32 v75, v75, 0x3e0293ee, v132
	v_fmamk_f32 v76, v76, 0x3e0293ee, v132
	v_fmamk_f32 v77, v77, 0x3e0293ee, v132
	v_fmamk_f32 v78, v78, 0x3e0293ee, v132
	v_fmamk_f32 v79, v79, 0x3e0293ee, v132
	v_fmamk_f32 v80, v80, 0x3e0293ee, v132
	v_fmamk_f32 v81, v81, 0x3e0293ee, v132
	v_fmamk_f32 v82, v82, 0x3e0293ee, v132
	v_fmac_f32_e32 v132, 0x3e0293ee, v83
	v_exp_f32_e32 v83, v84
	v_exp_f32_e32 v84, v85
	v_exp_f32_e32 v85, v86
	v_exp_f32_e32 v86, v87
	v_exp_f32_e32 v87, v88
	v_exp_f32_e32 v88, v89
	v_exp_f32_e32 v89, v90
	v_exp_f32_e32 v90, v91
	v_exp_f32_e32 v91, v92
	v_exp_f32_e32 v92, v93
	v_exp_f32_e32 v93, v94
	v_exp_f32_e32 v94, v95
	v_exp_f32_e32 v95, v96
	v_exp_f32_e32 v96, v97
	v_exp_f32_e32 v97, v98
	v_exp_f32_e32 v98, v99
	v_exp_f32_e32 v99, v132
	v_add_f32_e32 v132, 0, v83
	v_add_f32_e32 v132, v84, v132
	v_add_f32_e32 v132, v85, v132
	v_add_f32_e32 v132, v86, v132
	v_add_f32_e32 v132, v87, v132
	v_add_f32_e32 v132, v88, v132
	v_add_f32_e32 v132, v89, v132
	v_add_f32_e32 v132, v90, v132
	v_add_f32_e32 v132, v91, v132
	v_add_f32_e32 v132, v92, v132
	v_add_f32_e32 v132, v93, v132
	v_add_f32_e32 v132, v94, v132
	v_exp_f32_e32 v68, v68
	v_add_f32_e32 v132, v95, v132
	v_exp_f32_e32 v69, v69
	v_add_f32_e32 v132, v96, v132
	v_exp_f32_e32 v70, v70
	v_add_f32_e32 v132, v97, v132
	v_exp_f32_e32 v71, v71
	v_add_f32_e32 v132, v98, v132
	v_exp_f32_e32 v72, v72
	v_add_f32_e32 v132, v68, v132
	v_exp_f32_e32 v73, v73
	v_add_f32_e32 v132, v69, v132
	v_exp_f32_e32 v74, v74
	v_add_f32_e32 v132, v70, v132
	v_exp_f32_e32 v75, v75
	v_add_f32_e32 v132, v71, v132
	v_exp_f32_e32 v76, v76
	v_add_f32_e32 v132, v72, v132
	v_exp_f32_e32 v77, v77
	v_add_f32_e32 v132, v73, v132
	v_exp_f32_e32 v78, v78
	v_add_f32_e32 v132, v74, v132
	v_exp_f32_e32 v79, v79
	v_add_f32_e32 v132, v75, v132
	v_exp_f32_e32 v80, v80
	v_add_f32_e32 v132, v76, v132
	v_exp_f32_e32 v81, v81
	v_add_f32_e32 v132, v77, v132
	v_sub_f32_e32 v2, v182, v133
	v_exp_f32_e32 v82, v82
	v_add_f32_e32 v132, v78, v132
	v_mul_f32_e32 v2, 0x3e0293ee, v2
	v_add_f32_e32 v132, v79, v132
	v_exp_f32_e32 v2, v2
	v_add_f32_e32 v132, v80, v132
	v_add_f32_e32 v132, v81, v132
	v_add_f32_e32 v132, v82, v132
	v_add_f32_e32 v149, v99, v132
	v_cndmask_b32_e64 v2, v2, 1.0, vcc
	v_mov_b32_e32 v150, v149
	v_cvt_pk_bf16_f32 v132, v83, v84
	v_cvt_pk_bf16_f32 v133, v85, v86
	v_cvt_pk_bf16_f32 v134, v87, v88
	v_cvt_pk_bf16_f32 v135, v89, v90
	v_cvt_pk_bf16_f32 v136, v91, v92
	v_cvt_pk_bf16_f32 v137, v93, v94
	v_cvt_pk_bf16_f32 v138, v95, v96
	v_cvt_pk_bf16_f32 v139, v97, v98
	v_cvt_pk_bf16_f32 v140, v68, v69
	v_cvt_pk_bf16_f32 v141, v70, v71
	v_cvt_pk_bf16_f32 v142, v72, v73
	v_cvt_pk_bf16_f32 v143, v74, v75
	v_cvt_pk_bf16_f32 v144, v76, v77
	v_cvt_pk_bf16_f32 v145, v78, v79
	v_cvt_pk_bf16_f32 v146, v80, v81
	v_cvt_pk_bf16_f32 v147, v82, v99
	s_nop 1
	v_permlane32_swap_b32_e32 v149, v150
	v_cmp_gt_f32_e32 vcc, 1.0, v2
	s_cbranch_vccz .LBB0_641
	s_and_saveexec_b64 s[16:17], s[38:39]
	ds_write_b32 v172, v2 offset:128
	s_or_b64 exec, exec, s[16:17]
	s_waitcnt lgkmcnt(0)
	v_add_u32_e32 v80, v171, v168
	ds_read_b128 v[68:71], v80 offset:224
	ds_read_b128 v[72:75], v80 offset:192
	ds_read_b128 v[76:79], v80 offset:160
	ds_read_b128 v[80:83], v80 offset:128
	s_waitcnt lgkmcnt(3)
	v_pk_mul_f32 v[16:17], v[16:17], v[68:69]
	s_waitcnt lgkmcnt(2)
	v_pk_mul_f32 v[12:13], v[12:13], v[72:73]
	s_waitcnt lgkmcnt(1)
	v_pk_mul_f32 v[8:9], v[8:9], v[76:77]
	v_pk_mul_f32 v[18:19], v[18:19], v[70:71]
	v_pk_mul_f32 v[14:15], v[14:15], v[74:75]
	v_pk_mul_f32 v[10:11], v[10:11], v[78:79]
	s_waitcnt lgkmcnt(0)
	v_pk_mul_f32 v[6:7], v[6:7], v[82:83]
	v_pk_mul_f32 v[4:5], v[4:5], v[80:81]
	v_pk_mul_f32 v[64:65], v[64:65], v[68:69]
	v_pk_mul_f32 v[60:61], v[60:61], v[72:73]
	v_pk_mul_f32 v[56:57], v[56:57], v[76:77]
	v_pk_mul_f32 v[66:67], v[66:67], v[70:71]
	v_pk_mul_f32 v[62:63], v[62:63], v[74:75]
	v_pk_mul_f32 v[58:59], v[58:59], v[78:79]
	v_pk_mul_f32 v[54:55], v[54:55], v[82:83]
	v_pk_mul_f32 v[52:53], v[52:53], v[80:81]
	v_pk_mul_f32 v[48:49], v[48:49], v[68:69]
	v_pk_mul_f32 v[44:45], v[44:45], v[72:73]
	v_pk_mul_f32 v[40:41], v[40:41], v[76:77]
	v_pk_mul_f32 v[50:51], v[50:51], v[70:71]
	v_pk_mul_f32 v[46:47], v[46:47], v[74:75]
	v_pk_mul_f32 v[42:43], v[42:43], v[78:79]
	v_pk_mul_f32 v[38:39], v[38:39], v[82:83]
	v_pk_mul_f32 v[36:37], v[36:37], v[80:81]
	v_pk_mul_f32 v[32:33], v[32:33], v[68:69]
	v_pk_mul_f32 v[28:29], v[28:29], v[72:73]
	v_pk_mul_f32 v[24:25], v[24:25], v[76:77]
	v_pk_mul_f32 v[34:35], v[34:35], v[70:71]
	v_pk_mul_f32 v[30:31], v[30:31], v[74:75]
	v_pk_mul_f32 v[26:27], v[26:27], v[78:79]
	v_pk_mul_f32 v[22:23], v[22:23], v[82:83]
	v_pk_mul_f32 v[20:21], v[20:21], v[80:81]
